# odd row-block classes (XCDs) start P1 and P8 about 20 us late so the two chip halves run their bandwidth-bound and MFMA-bound parts out of phase
# speedup vs baseline: 1.0015x; 1.0015x over previous
; #define BAR_LDS() do { asm volatile("s_waitcnt lgkmcnt(0)" ::: "memory"); __builtin_amdgcn_s_barrier(); asm volatile("" ::: "memory"); } while (0)
; #define lane (lane_now())
; __device__ __forceinline__ void norm_phase(const float* src, const float* g, const float* mod, int ish, int isc, bf16_t* dst, LAS unsigned char* lds, int gw, int ngw, int wave, int lane) {
;     ...
;     for (int i = wave * 64 + lane; i < 4096; i += 512) { const int b = i >> 10, c = i & 1023; GSl[i] = g[c] * (1.f + mod[(size_t)b * NMOD + isc * 1024 + c]); SHl[i] = mod[(size_t)b * NMOD + ish * 1024 + c]; }
;     BAR_LDS();
;     for (int m = gw; m < MTOK; m += ngw) {
;         const f32x4* xr = (const f32x4*)(src + (size_t)m * DM) + lane;
.LBB0_84:
	s_or_b64 exec, exec, s[6:7]
	s_waitcnt lgkmcnt(0)
	s_barrier
	s_cmp_lt_i32 s78, 0x8000
	s_cselect_b64 s[0:1], -1, 0
	s_cmpk_gt_i32 s78, 0x7fff
	v_mbcnt_lo_u32_b32 v204, -1, 0
	s_cbranch_scc1 .LBB0_87
	s_mov_b32 s100, s78
	s_mov_b32 s101, s84
	s_mov_b32 s98, 0x8000
	v_readlane_b32 s99, v244, 61
	s_cmp_eq_u32 s99, 0
	s_cbranch_scc1 .Lxn_keep86
	s_bitcmp1_b32 s100, 3
	s_cbranch_scc0 .Lstg1_done
	s_movk_i32 s99, 6
.Lstg1_loop:
	s_sleep 127
	s_sub_u32 s99, s99, 1
	s_cmp_lg_u32 s99, 0
	s_cbranch_scc1 .Lstg1_loop
.Lstg1_done:
	s_lshr_b32 s99, s100, 3
	s_and_b32 s98, s99, 7
	s_lshl_b32 s98, s98, 12
	s_and_b32 s99, s99, 0xfffffff8
	s_and_b32 s78, s100, 7
	s_add_i32 s78, s78, s99
	s_add_i32 s78, s78, s98
	s_add_i32 s98, s98, 0x1000
	s_movk_i32 s84, 0x100

; #define LAS __attribute__((address_space(3)))
; #define lane (lane_now())
; __device__ __forceinline__ void rwkv_out_ch(const Params& p, LAS unsigned char* ldsw, int ch, int lane) {
;     const int bh = ch >> 7, c = ch & 127, b = bh >> 3, h = bh & 7, fr = lane & 15, fq = lane >> 4;
;     const h16* base = (const h16*)(p.ws + WS_SC) + ((size_t)bh * SEQ + (size_t)c * 64) * 384;
;     const bf16_t* G = (const bf16_t*)(p.ws + WS_G); const float* SS = (const float*)(p.ws + WS_SS); bf16_t* MIX = (bf16_t*)(p.ws + WS_MIX);
;     LAS bf16_t* stg = (LAS bf16_t*)ldsw;
;     bf16x8 sf[4][2]; f32x4 lg[4], lb[4];
; #pragma unroll
;     for (int nt = 0; nt < 4; ++nt) {
; #pragma unroll
;         for (int ks = 0; ks < 2; ++ks) sf[nt][ks] = *(const bf16x8*)(base + (size_t)((16 * nt + fr) * 6 + 1) * 64 + ks * 32 + fq * 8);
;         const int cc = h * 64 + 16 * fq + 4 * nt; lg[nt] = *(const f32x4*)(p.lnx_g + cc); lb[nt] = *(const f32x4*)(p.lnx_b + cc);
;     }
;     bf16x8 rbfB[2][2]; f32x4 y0B[2][4]; u32x2 gB[2][4]; h16x4 vB[2][4]; float bonB[2];
; __global__ void __launch_bounds__(512, 2) mega_fwd(Params p) {
;     ...
;     { const int lane9 = lane; LAS unsigned char* ldsw = lds + wave * (16 * MS * 2); for (int it = gw; it < 32 * 128; it += ngw) rwkv_out_ch(p, ldsw, it, lane9); }
.LBB0_1096:
	v_readlane_b32 s0, v244, 31
	v_readlane_b32 s1, v244, 32
	s_andn2_b64 vcc, exec, s[0:1]
	s_waitcnt lgkmcnt(0)
	s_barrier
	v_mbcnt_lo_u32_b32 v0, -1, 0
	v_mbcnt_hi_u32_b32 v0, -1, v0
	s_cbranch_vccnz .LBB0_1099
	v_and_b32_e32 v6, 64, v166
	v_xor_b32_e32 v1, 16, v166
	v_add_u32_e32 v6, 64, v6
	v_cmp_lt_i32_e32 vcc, v1, v6
	s_add_u32 s0, s92, 0x4b00000
	s_mul_i32 s4, s69, 0x900
	v_cndmask_b32_e32 v1, v166, v1, vcc
	v_lshlrev_b32_e32 v151, 2, v1
	v_xor_b32_e32 v1, 32, v166
	v_cmp_lt_i32_e32 vcc, v1, v6
	v_and_b32_e32 v85, 15, v0
	v_and_b32_e32 v103, -16, v0
	v_cndmask_b32_e32 v1, v166, v1, vcc
	s_addc_u32 s1, s93, 0
	s_add_i32 s4, s4, 0
	v_ashrrev_i32_e32 v2, 4, v0
	v_lshlrev_b32_e32 v152, 2, v1
	s_movk_i32 s5, 0x90
	v_mul_u32_u24_e32 v1, 0x90, v85
	v_lshlrev_b32_e32 v6, 1, v103
	v_ashrrev_i32_e32 v66, 2, v0
	v_lshlrev_b32_e32 v0, 5, v0
	v_add3_u32 v153, s4, v1, v6
	v_mul_lo_u32 v1, v66, s5
	v_and_b32_e32 v0, 0x60, v0
	v_mul_u32_u24_e32 v3, 0x180, v85
	v_add3_u32 v154, s4, v1, v0
	v_mov_b32_e32 v1, 0
	v_lshl_add_u64 v[68:69], s[96:97], 0, v[0:1]
	v_lshlrev_b32_e32 v0, 1, v3
	v_ashrrev_i32_e32 v3, 31, v2
	v_lshlrev_b32_e32 v4, 2, v2
	v_lshlrev_b64 v[72:73], 3, v[2:3]
	v_lshlrev_b32_e32 v64, 3, v2
	v_ashrrev_i32_e32 v5, 31, v4
	v_sub_co_u32_e32 v74, vcc, 0, v72
	s_lshl_b32 s4, s68, 9
	s_mov_b32 s9, 0
	v_ashrrev_i32_e32 v65, 31, v64
	v_or_b32_e32 v150, 16, v85
	v_ashrrev_i32_e32 v67, 31, v66
	v_or_b32_e32 v155, 32, v85
	v_or_b32_e32 v156, 48, v85
	v_lshl_add_u64 v[70:71], s[6:7], 0, v[0:1]
	v_subb_co_u32_e32 v75, vcc, 0, v73, vcc
	s_add_i32 s28, s4, s86
	s_lshl_b32 s29, s94, 9
	v_mov_b32_e32 v157, 0x300
	s_mov_b64 s[6:7], 0x3000
	s_mov_b64 s[10:11], 0x6080
	s_movk_i32 s30, 0x6000
	s_mov_b64 s[12:13], 0x9080
	s_mov_b32 s31, 0x9000
	v_lshlrev_b64 v[76:77], 1, v[4:5]
	v_mov_b32_e32 v158, 0x3a27c5ac
	s_mov_b32 s34, 0x800000
	s_mov_b64 s[14:15], 0x6000
	s_mov_b64 s[16:17], 0x9000
	s_mov_b32 s35, s78
	s_mov_b32 s101, s84
	s_mov_b32 s98, 0x1000
	v_readlane_b32 s99, v244, 61
	s_cmp_eq_u32 s99, 0
	s_cbranch_scc1 .Lxo_keep
	s_bitcmp1_b32 s78, 3
	s_cbranch_scc0 .Lstg8_done
	s_movk_i32 s99, 6

; #define LAS __attribute__((address_space(3)))
; #define lane (lane_now())
; __global__ void __launch_bounds__(512, 2) mega_fwd(Params p) {
;     ...
;     { const int lane9 = lane; LAS unsigned char* ldsw = lds + wave * (16 * MS * 2); for (int it = gw; it < 32 * 128; it += ngw) rwkv_out_ch(p, ldsw, it, lane9); }
.Lstg8_done:
	s_lshr_b32 s99, s78, 3
	s_and_b32 s100, s99, 7
	s_lshr_b32 s99, s99, 3
	s_and_b32 s35, s100, 1
	s_lshl_b32 s35, s35, 6
	s_add_i32 s35, s35, s99
	s_lshr_b32 s100, s100, 1
	s_lshl_b32 s100, s100, 3
	s_and_b32 s99, s78, 7
	s_add_i32 s100, s100, s99
	s_lshl_b32 s100, s100, 7
	s_add_i32 s35, s35, s100
	s_lshl_b32 s28, s35, 6
	s_movk_i32 s29, 0x800
	s_movk_i32 s84, 32
	s_add_i32 s98, s35, 64
